# layer-0 RMSNorm rows: gain/shift/scale vector loads of column groups 1-3 hoisted (with their address arithmetic) to just after group 0's loads into spare registers by live-range renaming; single wait
# speedup vs baseline: 1.0255x; 1.0043x over previous
.LBB0_1076:
	s_or_b64 exec, exec, s[0:1]
	v_lshlrev_b32_e32 v1, 2, v1
	v_and_b32_e32 v47, 0xfc, v1
	v_lshlrev_b32_e32 v20, 2, v47
	v_mov_b32_e32 v21, v0
	v_lshl_add_u64 v[2:3], v[2:3], 0, v[20:21]
	global_load_dwordx4 v[14:17], v[2:3], off
	global_load_dwordx4 v[10:13], v[2:3], off offset:1024
	global_load_dwordx4 v[6:9], v[2:3], off offset:2048
	s_nop 0
	global_load_dwordx4 v[2:5], v[2:3], off offset:3072
	v_and_b32_e32 v1, 64, v195
	v_add_u32_e32 v251, 64, v1
	v_xor_b32_e32 v1, 32, v195
	v_cmp_lt_i32_e32 vcc, v1, v251
	v_xor_b32_e32 v252, 16, v195
	s_mov_b32 s0, 0x800000
	v_cndmask_b32_e32 v1, v195, v1, vcc
	v_cmp_lt_i32_e32 vcc, v252, v251
	v_lshlrev_b32_e32 v1, 2, v1
	v_readlane_b32 s36, v248, 6
	v_cndmask_b32_e32 v252, v195, v252, vcc
	v_lshlrev_b32_e32 v42, 2, v252
	v_xor_b32_e32 v252, 8, v195
	v_cmp_lt_i32_e32 vcc, v252, v251
	v_readlane_b32 s48, v248, 18
	v_readlane_b32 s49, v248, 19
	v_cndmask_b32_e32 v252, v195, v252, vcc
	v_lshlrev_b32_e32 v43, 2, v252
	v_xor_b32_e32 v252, 4, v195
	v_cmp_lt_i32_e32 vcc, v252, v251
	v_or_b32_e32 v33, 0x300, v47
	v_or_b32_e32 v37, 0x100, v47
	v_cndmask_b32_e32 v252, v195, v252, vcc
	v_lshlrev_b32_e32 v44, 2, v252
	v_xor_b32_e32 v252, 2, v195
	v_cmp_lt_i32_e32 vcc, v252, v251
	v_or_b32_e32 v36, 0x200, v47
	v_readlane_b32 s37, v248, 7
	v_cndmask_b32_e32 v252, v195, v252, vcc
	v_lshlrev_b32_e32 v45, 2, v252
	v_xor_b32_e32 v252, 1, v195
	v_cmp_lt_i32_e32 vcc, v252, v251
	v_readlane_b32 s38, v248, 8
	v_readlane_b32 s39, v248, 9
	v_cndmask_b32_e32 v251, v195, v252, vcc
	v_lshlrev_b32_e32 v46, 2, v251
	v_readlane_b32 s40, v248, 10
	v_readlane_b32 s41, v248, 11
	v_readlane_b32 s42, v248, 12
	v_readlane_b32 s43, v248, 13
	v_readlane_b32 s44, v248, 14
	v_readlane_b32 s45, v248, 15
	v_readlane_b32 s46, v248, 16
	s_nop 0
	v_readlane_b32 s47, v248, 17
	s_nop 0
	v_readlane_b32 s50, v248, 20
	s_nop 0
	v_readlane_b32 s51, v248, 21
	s_nop 0
	s_waitcnt vmcnt(3)
	s_waitcnt vmcnt(2)
	v_mul_f32_e32 v249, v15, v15
	v_mul_f32_e32 v250, v11, v11
	s_nop 0
	v_fma_f32 v251, v14, v14, v249
	v_fma_f32 v252, v10, v10, v250
	v_fma_f32 v251, v16, v16, v251
	v_fma_f32 v252, v12, v12, v252
	v_fma_f32 v26, v17, v17, v251
	v_fma_f32 v27, v13, v13, v252
	v_add_f32_e32 v26, v26, v27
	global_load_dwordx4 v[38:41], v20, s[48:49]
	s_waitcnt vmcnt(2)
	s_waitcnt vmcnt(1)
	v_mul_f32_e32 v30, v7, v7
	v_mul_f32_e32 v31, v3, v3
	s_nop 0
	v_fma_f32 v28, v6, v6, v30
	v_fma_f32 v29, v2, v2, v31
	v_fma_f32 v28, v8, v8, v28
	v_fma_f32 v29, v4, v4, v29
	v_fma_f32 v28, v9, v9, v28
	v_fma_f32 v29, v5, v5, v29
	s_nop 0
	v_add_f32_e32 v26, v26, v28
	v_add_f32_e32 v26, v26, v29
	ds_bpermute_b32 v27, v1, v26
	s_nop 2
	s_waitcnt lgkmcnt(0)
	v_add_f32_e32 v26, v26, v27
	ds_bpermute_b32 v27, v42, v26
	s_nop 2
	s_waitcnt lgkmcnt(0)
	v_add_f32_e32 v26, v26, v27
	ds_bpermute_b32 v27, v43, v26
	s_nop 2
	s_waitcnt lgkmcnt(0)
	v_add_f32_e32 v26, v26, v27
	ds_bpermute_b32 v27, v44, v26
	s_nop 2
	s_waitcnt lgkmcnt(0)
	v_add_f32_e32 v26, v26, v27
	ds_bpermute_b32 v27, v45, v26
	s_nop 2
	s_waitcnt lgkmcnt(0)
	v_add_f32_e32 v26, v26, v27
	ds_bpermute_b32 v27, v46, v26
	s_waitcnt lgkmcnt(0)
	v_add_f32_e32 v26, v26, v27
	v_fmamk_f32 v26, v26, 0x3a800000, v188
	v_cmp_gt_f32_e32 vcc, s0, v26
	v_readlane_b32 s0, v245, 5
	v_readlane_b32 s1, v245, 6
	v_mul_f32_e32 v27, 0x4b800000, v26
	v_cndmask_b32_e32 v26, v26, v27, vcc
	v_lshl_add_u64 v[22:23], v[22:23], 2, s[0:1]
	s_mov_b64 s[0:1], 0x1000
	v_lshl_add_u64 v[34:35], v[22:23], 0, s[0:1]
	v_lshl_add_u64 v[30:31], v[22:23], 0, v[20:21]
	v_lshl_add_u64 v[22:23], v[34:35], 0, v[20:21]
	global_load_dwordx4 v[48:51], v[30:31], off
	global_load_dwordx4 v[52:55], v[22:23], off
	global_load_dwordx4 v[64:67], v20, s[48:49] offset:1024
	global_load_dwordx4 v[68:71], v[30:31], off offset:1024
	v_lshlrev_b32_e32 v74, 2, v37
	v_mov_b32_e32 v75, v0
	v_lshl_add_u64 v[72:73], v[34:35], 0, v[74:75]
	global_load_dwordx4 v[76:79], v[72:73], off
	global_load_dwordx4 v[80:83], v20, s[48:49] offset:2048
	global_load_dwordx4 v[84:87], v[30:31], off offset:2048
	v_lshlrev_b32_e32 v90, 2, v36
	v_mov_b32_e32 v91, v0
	v_lshl_add_u64 v[88:89], v[34:35], 0, v[90:91]
	global_load_dwordx4 v[92:95], v[88:89], off
	global_load_dwordx4 v[96:99], v20, s[48:49] offset:3072
	global_load_dwordx4 v[100:103], v[30:31], off offset:3072
	v_lshlrev_b32_e32 v106, 2, v33
	v_mov_b32_e32 v107, v0
	v_lshl_add_u64 v[104:105], v[34:35], 0, v[106:107]
	global_load_dwordx4 v[108:111], v[104:105], off
	v_rsq_f32_e32 v26, v26
	v_readlane_b32 s0, v247, 56
	v_readlane_b32 s1, v247, 57
	v_mul_f32_e32 v27, 0x45800000, v26
	v_cndmask_b32_e32 v32, v26, v27, vcc
	v_pk_mul_f32 v[14:15], v[14:15], v[32:33] op_sel_hi:[1,0]
	v_lshlrev_b64 v[26:27], 11, v[24:25]
	s_waitcnt vmcnt(0)
	v_pk_mul_f32 v[14:15], v[38:39], v[14:15]
	v_lshl_add_u64 v[26:27], s[0:1], 0, v[26:27]
	v_pk_mul_f32 v[10:11], v[10:11], v[32:33] op_sel_hi:[1,0]
	v_pk_mul_f32 v[12:13], v[12:13], v[32:33] op_sel_hi:[1,0]
	v_pk_mul_f32 v[6:7], v[6:7], v[32:33] op_sel_hi:[1,0]
	v_pk_mul_f32 v[8:9], v[8:9], v[32:33] op_sel_hi:[1,0]
	v_pk_mul_f32 v[2:3], v[2:3], v[32:33] op_sel_hi:[1,0]
	v_pk_mul_f32 v[4:5], v[4:5], v[32:33] op_sel_hi:[1,0]
	s_nop 0
	v_pk_add_f32 v[22:23], v[52:53], 1.0 op_sel_hi:[1,0]
	s_nop 0
	v_pk_fma_f32 v[14:15], v[22:23], v[14:15], v[48:49]
	v_lshlrev_b32_e32 v22, 1, v47
	v_cvt_pk_bf16_f32 v28, v14, v15
	v_pk_mul_f32 v[14:15], v[16:17], v[32:33] op_sel_hi:[1,0]
	v_pk_add_f32 v[16:17], v[54:55], 1.0 op_sel_hi:[1,0]
	v_pk_mul_f32 v[14:15], v[40:41], v[14:15]
	v_mov_b32_e32 v23, v0
	v_pk_fma_f32 v[14:15], v[16:17], v[14:15], v[50:51]
	s_nop 0
	v_cvt_pk_bf16_f32 v29, v14, v15
	v_lshl_add_u64 v[14:15], v[26:27], 0, v[22:23]
	v_lshlrev_b32_e32 v26, 2, v37
	v_mov_b32_e32 v27, v0
	global_store_dwordx2 v[14:15], v[28:29], off
	v_lshl_add_u64 v[16:17], v[34:35], 0, v[26:27]
	v_lshlrev_b32_e32 v28, 2, v36
	v_mov_b32_e32 v29, v0
	s_nop 0
	v_pk_mul_f32 v[10:11], v[64:65], v[10:11]
	v_pk_mul_f32 v[12:13], v[66:67], v[12:13]
	s_nop 0
	v_pk_add_f32 v[16:17], v[76:77], 1.0 op_sel_hi:[1,0]
	s_nop 0
	v_pk_fma_f32 v[10:11], v[16:17], v[10:11], v[68:69]
	v_pk_add_f32 v[16:17], v[78:79], 1.0 op_sel_hi:[1,0]
	v_cvt_pk_bf16_f32 v10, v10, v11
	v_pk_fma_f32 v[12:13], v[16:17], v[12:13], v[70:71]
	v_lshl_add_u64 v[16:17], v[34:35], 0, v[28:29]
	v_cvt_pk_bf16_f32 v11, v12, v13
	global_store_dwordx2 v[14:15], v[10:11], off offset:512
	s_nop 0
	s_nop 0
	v_pk_mul_f32 v[6:7], v[80:81], v[6:7]
	v_pk_mul_f32 v[8:9], v[82:83], v[8:9]
	s_nop 0
	v_pk_add_f32 v[10:11], v[92:93], 1.0 op_sel_hi:[1,0]
	s_nop 0
	v_pk_fma_f32 v[6:7], v[10:11], v[6:7], v[84:85]
	v_pk_add_f32 v[10:11], v[94:95], 1.0 op_sel_hi:[1,0]
	v_cvt_pk_bf16_f32 v6, v6, v7
	v_pk_fma_f32 v[8:9], v[10:11], v[8:9], v[86:87]
	v_or_b32_e32 v38, 1, v24
	v_cvt_pk_bf16_f32 v7, v8, v9
	global_store_dwordx2 v[14:15], v[6:7], off offset:1024
	s_nop 0
	v_lshlrev_b32_e32 v30, 2, v33
	v_mov_b32_e32 v31, v0
	v_lshl_add_u64 v[16:17], v[34:35], 0, v[30:31]
	v_cmp_lt_i32_e32 vcc, s4, v38
	s_nop 0
	v_pk_mul_f32 v[2:3], v[96:97], v[2:3]
	v_pk_mul_f32 v[4:5], v[98:99], v[4:5]
	s_nop 0
	v_pk_add_f32 v[6:7], v[108:109], 1.0 op_sel_hi:[1,0]
	s_nop 0
	v_pk_fma_f32 v[2:3], v[2:3], v[6:7], v[100:101]
	v_pk_add_f32 v[6:7], v[110:111], 1.0 op_sel_hi:[1,0]
	v_cvt_pk_bf16_f32 v2, v2, v3
	v_pk_fma_f32 v[4:5], v[4:5], v[6:7], v[102:103]
	s_nop 0
	v_cvt_pk_bf16_f32 v3, v4, v5
	global_store_dwordx2 v[14:15], v[2:3], off offset:1536
	s_and_saveexec_b64 s[0:1], vcc
	s_xor_b64 s[0:1], exec, s[0:1]
	s_cbranch_execz .LBB0_1078
	v_add_u32_e32 v2, 0xffffe001, v24
	v_mov_b32_e32 v3, v0
	v_readlane_b32 s36, v248, 6
	v_lshlrev_b64 v[2:3], 12, v[2:3]
	v_readlane_b32 s38, v248, 8
	v_readlane_b32 s39, v248, 9
	v_mov_b32_e32 v39, v0
	v_readlane_b32 s37, v248, 7
	v_lshl_add_u64 v[2:3], s[38:39], 0, v[2:3]
	v_readlane_b32 s40, v248, 10
	v_readlane_b32 s41, v248, 11
	v_readlane_b32 s42, v248, 12
	v_readlane_b32 s43, v248, 13
	v_readlane_b32 s44, v248, 14
	v_readlane_b32 s45, v248, 15
	v_readlane_b32 s46, v248, 16
	v_readlane_b32 s47, v248, 17
	v_readlane_b32 s48, v248, 18
	v_readlane_b32 s49, v248, 19
	v_readlane_b32 s50, v248, 20
	v_readlane_b32 s51, v248, 21

.LBB0_1080:
	s_or_b64 exec, exec, s[0:1]
	v_readlane_b32 s36, v248, 6
	v_readlane_b32 s48, v248, 18
	v_readlane_b32 s49, v248, 19
	s_mov_b32 s0, 0x800000
	v_lshlrev_b64 v[38:39], 11, v[38:39]
	v_lshl_add_u64 v[32:33], s[48:49], 0, v[20:21]
	v_mov_b32_e32 v21, v0
	v_lshl_add_u64 v[2:3], v[2:3], 0, v[20:21]
	global_load_dwordx4 v[14:17], v[2:3], off
	global_load_dwordx4 v[10:13], v[2:3], off offset:1024
	global_load_dwordx4 v[6:9], v[2:3], off offset:2048
	s_nop 0
	global_load_dwordx4 v[2:5], v[2:3], off offset:3072
	v_mov_b32_e32 v27, v0
	v_mov_b32_e32 v29, v0
	v_mov_b32_e32 v31, v0
	v_readlane_b32 s43, v248, 13
	s_movk_i32 s43, 0x1fff
	v_readlane_b32 s37, v248, 7
	v_readlane_b32 s38, v248, 8
	v_readlane_b32 s39, v248, 9
	v_readlane_b32 s40, v248, 10
	v_readlane_b32 s41, v248, 11
	v_readlane_b32 s42, v248, 12
	v_readlane_b32 s44, v248, 14
	v_readlane_b32 s45, v248, 15
	v_readlane_b32 s46, v248, 16
	s_nop 0
	v_readlane_b32 s47, v248, 17
	s_nop 0
	v_readlane_b32 s50, v248, 20
	s_nop 0
	v_readlane_b32 s51, v248, 21
	s_nop 0
	s_waitcnt vmcnt(3)
	s_waitcnt vmcnt(2)
	v_mul_f32_e32 v249, v15, v15
	v_mul_f32_e32 v250, v11, v11
	s_nop 0
	v_fma_f32 v251, v14, v14, v249
	v_fma_f32 v252, v10, v10, v250
	v_fma_f32 v251, v16, v16, v251
	v_fma_f32 v252, v12, v12, v252
	v_fma_f32 v34, v17, v17, v251
	v_fma_f32 v35, v13, v13, v252
	v_add_f32_e32 v23, v34, v35
	s_waitcnt vmcnt(1)
	s_waitcnt vmcnt(0)
	v_mul_f32_e32 v48, v7, v7
	v_mul_f32_e32 v49, v3, v3
	s_nop 0
	v_fma_f32 v40, v6, v6, v48
	v_fma_f32 v41, v2, v2, v49
	v_fma_f32 v40, v8, v8, v40
	v_fma_f32 v41, v4, v4, v41
	v_fma_f32 v40, v9, v9, v40
	v_fma_f32 v41, v5, v5, v41
	global_load_dwordx4 v[48:51], v[32:33], off
	v_add_f32_e32 v23, v23, v40
	v_add_f32_e32 v23, v23, v41
	ds_bpermute_b32 v25, v1, v23
	s_nop 2
	s_waitcnt lgkmcnt(0)
	v_add_f32_e32 v23, v23, v25
	ds_bpermute_b32 v25, v42, v23
	s_nop 2
	s_waitcnt lgkmcnt(0)
	v_add_f32_e32 v23, v23, v25
	ds_bpermute_b32 v25, v43, v23
	s_nop 2
	s_waitcnt lgkmcnt(0)
	v_add_f32_e32 v23, v23, v25
	ds_bpermute_b32 v25, v44, v23
	s_nop 2
	s_waitcnt lgkmcnt(0)
	v_add_f32_e32 v23, v23, v25
	ds_bpermute_b32 v25, v45, v23
	s_nop 2
	s_waitcnt lgkmcnt(0)
	v_add_f32_e32 v23, v23, v25
	ds_bpermute_b32 v25, v46, v23
	s_waitcnt lgkmcnt(0)
	v_add_f32_e32 v23, v23, v25
	v_fmamk_f32 v23, v23, 0x3a800000, v188
	v_cmp_gt_f32_e32 vcc, s0, v23
	v_readlane_b32 s0, v245, 5
	v_readlane_b32 s1, v245, 6
	v_mul_f32_e32 v25, 0x4b800000, v23
	v_cndmask_b32_e32 v23, v23, v25, vcc
	v_lshl_add_u64 v[52:53], v[36:37], 2, s[0:1]
	s_mov_b64 s[0:1], 0x1000
	v_lshl_add_u64 v[36:37], v[52:53], 0, s[0:1]
	v_readlane_b32 s0, v247, 56
	v_readlane_b32 s1, v247, 57
	v_lshl_add_u64 v[56:57], v[36:37], 0, v[20:21]
	global_load_dwordx4 v[56:59], v[56:57], off
	v_lshl_add_u64 v[40:41], s[0:1], 0, v[38:39]
	v_lshl_add_u64 v[38:39], v[52:53], 0, v[20:21]
	global_load_dwordx4 v[52:55], v[38:39], off
	global_load_dwordx4 v[64:67], v[32:33], off offset:1024
	global_load_dwordx4 v[68:71], v[38:39], off offset:1024
	v_lshl_add_u64 v[72:73], v[36:37], 0, v[26:27]
	global_load_dwordx4 v[74:77], v[72:73], off
	global_load_dwordx4 v[78:81], v[32:33], off offset:2048
	global_load_dwordx4 v[82:85], v[38:39], off offset:2048
	v_lshl_add_u64 v[86:87], v[36:37], 0, v[28:29]
	global_load_dwordx4 v[88:91], v[86:87], off
	global_load_dwordx4 v[92:95], v[32:33], off offset:3072
	global_load_dwordx4 v[96:99], v[38:39], off offset:3072
	v_lshl_add_u64 v[100:101], v[36:37], 0, v[30:31]
	global_load_dwordx4 v[102:105], v[100:101], off
	v_rsq_f32_e32 v23, v23
	s_nop 0
	v_mul_f32_e32 v25, 0x45800000, v23
	v_cndmask_b32_e32 v34, v23, v25, vcc
	v_pk_mul_f32 v[14:15], v[14:15], v[34:35] op_sel_hi:[1,0]
	v_mov_b32_e32 v23, v0
	v_pk_mul_f32 v[10:11], v[10:11], v[34:35] op_sel_hi:[1,0]
	v_pk_mul_f32 v[12:13], v[12:13], v[34:35] op_sel_hi:[1,0]
	v_pk_mul_f32 v[6:7], v[6:7], v[34:35] op_sel_hi:[1,0]
	v_pk_mul_f32 v[8:9], v[8:9], v[34:35] op_sel_hi:[1,0]
	v_pk_mul_f32 v[2:3], v[2:3], v[34:35] op_sel_hi:[1,0]
	v_pk_mul_f32 v[4:5], v[4:5], v[34:35] op_sel_hi:[1,0]
	s_waitcnt vmcnt(0)
	v_pk_mul_f32 v[14:15], v[48:49], v[14:15]
	s_nop 0
	v_pk_add_f32 v[48:49], v[56:57], 1.0 op_sel_hi:[1,0]
	s_nop 0
	v_pk_fma_f32 v[14:15], v[48:49], v[14:15], v[52:53]
	s_nop 0
	v_cvt_pk_bf16_f32 v48, v14, v15
	v_pk_mul_f32 v[14:15], v[16:17], v[34:35] op_sel_hi:[1,0]
	v_pk_add_f32 v[16:17], v[58:59], 1.0 op_sel_hi:[1,0]
	v_pk_mul_f32 v[14:15], v[50:51], v[14:15]
	s_nop 0
	v_pk_fma_f32 v[14:15], v[16:17], v[14:15], v[54:55]
	v_lshl_add_u64 v[16:17], v[36:37], 0, v[26:27]
	v_cvt_pk_bf16_f32 v49, v14, v15
	v_lshl_add_u64 v[14:15], v[40:41], 0, v[22:23]
	global_store_dwordx2 v[14:15], v[48:49], off
	s_nop 0
	s_nop 0
	v_pk_mul_f32 v[10:11], v[64:65], v[10:11]
	v_pk_mul_f32 v[12:13], v[66:67], v[12:13]
	s_nop 0
	v_pk_add_f32 v[16:17], v[74:75], 1.0 op_sel_hi:[1,0]
	s_nop 0
	v_pk_fma_f32 v[10:11], v[16:17], v[10:11], v[68:69]
	v_pk_add_f32 v[16:17], v[76:77], 1.0 op_sel_hi:[1,0]
	v_cvt_pk_bf16_f32 v10, v10, v11
	v_pk_fma_f32 v[12:13], v[16:17], v[12:13], v[70:71]
	v_lshl_add_u64 v[16:17], v[36:37], 0, v[28:29]
	v_cvt_pk_bf16_f32 v11, v12, v13
	global_store_dwordx2 v[14:15], v[10:11], off offset:512
	s_nop 0
	v_lshl_add_u64 v[16:17], v[36:37], 0, v[30:31]
	s_nop 0
	v_pk_mul_f32 v[6:7], v[78:79], v[6:7]
	v_pk_mul_f32 v[8:9], v[80:81], v[8:9]
	s_nop 0
	v_pk_add_f32 v[10:11], v[88:89], 1.0 op_sel_hi:[1,0]
	s_nop 0
	v_pk_fma_f32 v[6:7], v[10:11], v[6:7], v[82:83]
	v_pk_add_f32 v[10:11], v[90:91], 1.0 op_sel_hi:[1,0]
	v_cvt_pk_bf16_f32 v6, v6, v7
	v_pk_fma_f32 v[8:9], v[10:11], v[8:9], v[84:85]
	s_nop 0
	v_cvt_pk_bf16_f32 v7, v8, v9
	global_store_dwordx2 v[14:15], v[6:7], off offset:1024
	s_nop 0
	s_nop 0
	v_pk_mul_f32 v[2:3], v[92:93], v[2:3]
	v_pk_mul_f32 v[4:5], v[94:95], v[4:5]
	s_nop 0
	v_pk_add_f32 v[6:7], v[102:103], 1.0 op_sel_hi:[1,0]
	s_nop 0
	v_pk_fma_f32 v[2:3], v[2:3], v[6:7], v[96:97]
	v_pk_add_f32 v[6:7], v[104:105], 1.0 op_sel_hi:[1,0]
	v_or_b32_e32 v38, 2, v24
	v_pk_fma_f32 v[4:5], v[4:5], v[6:7], v[98:99]
	v_cvt_pk_bf16_f32 v2, v2, v3
	v_cvt_pk_bf16_f32 v3, v4, v5
	v_cmp_lt_i32_e32 vcc, s43, v38
	global_store_dwordx2 v[14:15], v[2:3], off offset:1536
	s_and_saveexec_b64 s[0:1], vcc
	s_xor_b64 s[0:1], exec, s[0:1]
	s_cbranch_execz .LBB0_1082
	v_add_u32_e32 v2, 0xffffe002, v24
	v_mov_b32_e32 v3, v0
	v_readlane_b32 s36, v248, 6
	v_lshlrev_b64 v[2:3], 12, v[2:3]
	v_readlane_b32 s38, v248, 8
	v_readlane_b32 s39, v248, 9
	v_readlane_b32 s43, v248, 13
	s_movk_i32 s43, 0x1fff
	v_lshl_add_u64 v[2:3], s[38:39], 0, v[2:3]
	v_mov_b32_e32 v39, v0
	v_readlane_b32 s37, v248, 7
	v_readlane_b32 s40, v248, 10
	v_readlane_b32 s41, v248, 11
	v_readlane_b32 s42, v248, 12
	v_readlane_b32 s44, v248, 14
	v_readlane_b32 s45, v248, 15
	v_readlane_b32 s46, v248, 16
	v_readlane_b32 s47, v248, 17
	v_readlane_b32 s48, v248, 18
	v_readlane_b32 s49, v248, 19
	v_readlane_b32 s50, v248, 20
	v_readlane_b32 s51, v248, 21

.LBB0_1084:
	s_or_b64 exec, exec, s[0:1]
	v_mov_b32_e32 v21, v0
	v_lshl_add_u64 v[2:3], v[2:3], 0, v[20:21]
	global_load_dwordx4 v[14:17], v[2:3], off
	global_load_dwordx4 v[10:13], v[2:3], off offset:1024
	global_load_dwordx4 v[6:9], v[2:3], off offset:2048
	s_nop 0
	global_load_dwordx4 v[2:5], v[2:3], off offset:3072
	s_mov_b32 s0, 0x800000
	v_lshlrev_b64 v[38:39], 11, v[38:39]
	v_mov_b32_e32 v27, v0
	v_mov_b32_e32 v29, v0
	v_mov_b32_e32 v31, v0
	s_waitcnt vmcnt(3)
	s_waitcnt vmcnt(2)
	v_mul_f32_e32 v249, v15, v15
	v_mul_f32_e32 v250, v11, v11
	s_nop 0
	v_fma_f32 v251, v14, v14, v249
	v_fma_f32 v252, v10, v10, v250
	v_fma_f32 v251, v16, v16, v251
	v_fma_f32 v252, v12, v12, v252
	v_fma_f32 v34, v17, v17, v251
	v_fma_f32 v35, v13, v13, v252
	v_add_f32_e32 v23, v34, v35
	s_waitcnt vmcnt(1)
	s_waitcnt vmcnt(0)
	v_mul_f32_e32 v48, v7, v7
	v_mul_f32_e32 v49, v3, v3
	s_nop 0
	v_fma_f32 v40, v6, v6, v48
	v_fma_f32 v41, v2, v2, v49
	v_fma_f32 v40, v8, v8, v40
	v_fma_f32 v41, v4, v4, v41
	v_fma_f32 v40, v9, v9, v40
	v_fma_f32 v41, v5, v5, v41
	global_load_dwordx4 v[48:51], v[32:33], off
	v_add_f32_e32 v23, v23, v40
	v_add_f32_e32 v23, v23, v41
	ds_bpermute_b32 v25, v1, v23
	s_nop 2
	s_waitcnt lgkmcnt(0)
	v_add_f32_e32 v23, v23, v25
	ds_bpermute_b32 v25, v42, v23
	s_nop 2
	s_waitcnt lgkmcnt(0)
	v_add_f32_e32 v23, v23, v25
	ds_bpermute_b32 v25, v43, v23
	s_nop 2
	s_waitcnt lgkmcnt(0)
	v_add_f32_e32 v23, v23, v25
	ds_bpermute_b32 v25, v44, v23
	s_nop 2
	s_waitcnt lgkmcnt(0)
	v_add_f32_e32 v23, v23, v25
	ds_bpermute_b32 v25, v45, v23
	s_nop 2
	s_waitcnt lgkmcnt(0)
	v_add_f32_e32 v23, v23, v25
	ds_bpermute_b32 v25, v46, v23
	s_waitcnt lgkmcnt(0)
	v_add_f32_e32 v23, v23, v25
	v_fmamk_f32 v23, v23, 0x3a800000, v188
	v_cmp_gt_f32_e32 vcc, s0, v23
	v_readlane_b32 s0, v245, 5
	v_readlane_b32 s1, v245, 6
	v_mul_f32_e32 v25, 0x4b800000, v23
	v_cndmask_b32_e32 v23, v23, v25, vcc
	v_lshl_add_u64 v[52:53], v[36:37], 2, s[0:1]
	s_mov_b64 s[0:1], 0x1000
	v_lshl_add_u64 v[36:37], v[52:53], 0, s[0:1]
	v_readlane_b32 s0, v247, 56
	v_readlane_b32 s1, v247, 57
	v_lshl_add_u64 v[56:57], v[36:37], 0, v[20:21]
	global_load_dwordx4 v[56:59], v[56:57], off
	v_lshl_add_u64 v[40:41], s[0:1], 0, v[38:39]
	v_lshl_add_u64 v[38:39], v[52:53], 0, v[20:21]
	global_load_dwordx4 v[52:55], v[38:39], off
	global_load_dwordx4 v[64:67], v[32:33], off offset:1024
	global_load_dwordx4 v[68:71], v[38:39], off offset:1024
	v_lshl_add_u64 v[72:73], v[36:37], 0, v[26:27]
	global_load_dwordx4 v[74:77], v[72:73], off
	global_load_dwordx4 v[78:81], v[32:33], off offset:2048
	global_load_dwordx4 v[82:85], v[38:39], off offset:2048
	v_lshl_add_u64 v[86:87], v[36:37], 0, v[28:29]
	global_load_dwordx4 v[88:91], v[86:87], off
	global_load_dwordx4 v[92:95], v[32:33], off offset:3072
	global_load_dwordx4 v[96:99], v[38:39], off offset:3072
	v_lshl_add_u64 v[100:101], v[36:37], 0, v[30:31]
	global_load_dwordx4 v[102:105], v[100:101], off
	v_rsq_f32_e32 v23, v23
	s_nop 0
	v_mul_f32_e32 v25, 0x45800000, v23
	v_cndmask_b32_e32 v34, v23, v25, vcc
	v_pk_mul_f32 v[14:15], v[14:15], v[34:35] op_sel_hi:[1,0]
	v_mov_b32_e32 v23, v0
	v_pk_mul_f32 v[10:11], v[10:11], v[34:35] op_sel_hi:[1,0]
	v_pk_mul_f32 v[12:13], v[12:13], v[34:35] op_sel_hi:[1,0]
	v_pk_mul_f32 v[6:7], v[6:7], v[34:35] op_sel_hi:[1,0]
	v_pk_mul_f32 v[8:9], v[8:9], v[34:35] op_sel_hi:[1,0]
	v_pk_mul_f32 v[2:3], v[2:3], v[34:35] op_sel_hi:[1,0]
	v_pk_mul_f32 v[4:5], v[4:5], v[34:35] op_sel_hi:[1,0]
	s_waitcnt vmcnt(0)
	v_pk_mul_f32 v[14:15], v[48:49], v[14:15]
	s_nop 0
	v_pk_add_f32 v[48:49], v[56:57], 1.0 op_sel_hi:[1,0]
	s_nop 0
	v_pk_fma_f32 v[14:15], v[48:49], v[14:15], v[52:53]
	s_nop 0
	v_cvt_pk_bf16_f32 v48, v14, v15
	v_pk_mul_f32 v[14:15], v[16:17], v[34:35] op_sel_hi:[1,0]
	v_pk_add_f32 v[16:17], v[58:59], 1.0 op_sel_hi:[1,0]
	v_pk_mul_f32 v[14:15], v[50:51], v[14:15]
	v_or_b32_e32 v34, 3, v24
	v_pk_fma_f32 v[14:15], v[16:17], v[14:15], v[54:55]
	v_lshl_add_u64 v[16:17], v[36:37], 0, v[26:27]
	v_cvt_pk_bf16_f32 v49, v14, v15
	v_lshl_add_u64 v[14:15], v[40:41], 0, v[22:23]
	global_store_dwordx2 v[14:15], v[48:49], off
	s_nop 0
	v_cmp_lt_i32_e32 vcc, s43, v34
	s_nop 0
	v_pk_mul_f32 v[10:11], v[64:65], v[10:11]
	v_pk_mul_f32 v[12:13], v[66:67], v[12:13]
	s_nop 0
	v_pk_add_f32 v[16:17], v[74:75], 1.0 op_sel_hi:[1,0]
	s_nop 0
	v_pk_fma_f32 v[10:11], v[16:17], v[10:11], v[68:69]
	v_pk_add_f32 v[16:17], v[76:77], 1.0 op_sel_hi:[1,0]
	v_cvt_pk_bf16_f32 v10, v10, v11
	v_pk_fma_f32 v[12:13], v[16:17], v[12:13], v[70:71]
	v_lshl_add_u64 v[16:17], v[36:37], 0, v[28:29]
	v_cvt_pk_bf16_f32 v11, v12, v13
	global_store_dwordx2 v[14:15], v[10:11], off offset:512
	s_nop 0
	v_lshl_add_u64 v[16:17], v[36:37], 0, v[30:31]
	s_nop 0
	v_pk_mul_f32 v[6:7], v[78:79], v[6:7]
	v_pk_mul_f32 v[8:9], v[80:81], v[8:9]
	s_nop 0
	v_pk_add_f32 v[10:11], v[88:89], 1.0 op_sel_hi:[1,0]
	s_nop 0
	v_pk_fma_f32 v[6:7], v[10:11], v[6:7], v[82:83]
	v_pk_add_f32 v[10:11], v[90:91], 1.0 op_sel_hi:[1,0]
	v_cvt_pk_bf16_f32 v6, v6, v7
	v_pk_fma_f32 v[8:9], v[10:11], v[8:9], v[84:85]
	s_nop 0
	v_cvt_pk_bf16_f32 v7, v8, v9
	global_store_dwordx2 v[14:15], v[6:7], off offset:1024
	s_nop 0
	s_nop 0
	v_pk_mul_f32 v[2:3], v[92:93], v[2:3]
	v_pk_mul_f32 v[4:5], v[94:95], v[4:5]
	s_nop 0
	v_pk_add_f32 v[6:7], v[102:103], 1.0 op_sel_hi:[1,0]
	s_nop 0
	v_pk_fma_f32 v[2:3], v[2:3], v[6:7], v[96:97]
	v_pk_add_f32 v[6:7], v[104:105], 1.0 op_sel_hi:[1,0]
	v_cvt_pk_bf16_f32 v2, v2, v3
	v_pk_fma_f32 v[4:5], v[4:5], v[6:7], v[98:99]
	s_nop 0
	v_cvt_pk_bf16_f32 v3, v4, v5
	global_store_dwordx2 v[14:15], v[2:3], off offset:1536
	s_and_saveexec_b64 s[0:1], vcc
	s_xor_b64 s[0:1], exec, s[0:1]
	s_cbranch_execz .LBB0_1086
	v_add_u32_e32 v2, 0xffffe003, v24
	v_mov_b32_e32 v3, v0
	v_readlane_b32 s36, v248, 6
	v_lshlrev_b64 v[2:3], 12, v[2:3]
	v_readlane_b32 s38, v248, 8
	v_readlane_b32 s39, v248, 9
	v_readlane_b32 s43, v248, 13
	s_movk_i32 s43, 0x1fff
	v_lshl_add_u64 v[2:3], s[38:39], 0, v[2:3]
	v_mov_b32_e32 v35, v0
	v_readlane_b32 s37, v248, 7
	v_readlane_b32 s40, v248, 10
	v_readlane_b32 s41, v248, 11
	v_readlane_b32 s42, v248, 12
	v_readlane_b32 s44, v248, 14
	v_readlane_b32 s45, v248, 15
	v_readlane_b32 s46, v248, 16
	v_readlane_b32 s47, v248, 17
	v_readlane_b32 s48, v248, 18
	v_readlane_b32 s49, v248, 19
	v_readlane_b32 s50, v248, 20
	v_readlane_b32 s51, v248, 21

.LBB0_1088:
	s_or_b64 exec, exec, s[0:1]
	v_mov_b32_e32 v21, v0
	v_lshl_add_u64 v[2:3], v[2:3], 0, v[20:21]
	global_load_dwordx4 v[14:17], v[2:3], off
	global_load_dwordx4 v[10:13], v[2:3], off offset:1024
	global_load_dwordx4 v[6:9], v[2:3], off offset:2048
	s_nop 0
	global_load_dwordx4 v[2:5], v[2:3], off offset:3072
	s_mov_b32 s0, 0x800000
	v_lshlrev_b64 v[34:35], 11, v[34:35]
	v_mov_b32_e32 v27, v0
	v_mov_b32_e32 v29, v0
	v_mov_b32_e32 v31, v0
	s_waitcnt vmcnt(3)
	s_waitcnt vmcnt(2)
	v_mul_f32_e32 v249, v15, v15
	v_mul_f32_e32 v250, v11, v11
	s_nop 0
	v_fma_f32 v251, v14, v14, v249
	v_fma_f32 v252, v10, v10, v250
	v_fma_f32 v251, v16, v16, v251
	v_fma_f32 v252, v12, v12, v252
	v_fma_f32 v24, v17, v17, v251
	v_fma_f32 v25, v13, v13, v252
	v_add_f32_e32 v23, v24, v25
	s_waitcnt vmcnt(1)
	s_waitcnt vmcnt(0)
	v_mul_f32_e32 v38, v7, v7
	v_mul_f32_e32 v39, v3, v3
	s_nop 0
	v_fma_f32 v36, v6, v6, v38
	v_fma_f32 v37, v2, v2, v39
	v_fma_f32 v36, v8, v8, v36
	v_fma_f32 v37, v4, v4, v37
	v_fma_f32 v36, v9, v9, v36
	v_fma_f32 v37, v5, v5, v37
	global_load_dwordx4 v[38:41], v[32:33], off
	v_add_f32_e32 v23, v23, v36
	v_add_f32_e32 v23, v23, v37
	ds_bpermute_b32 v1, v1, v23
	s_nop 2
	s_waitcnt lgkmcnt(0)
	v_add_f32_e32 v1, v23, v1
	ds_bpermute_b32 v23, v42, v1
	s_nop 2
	s_waitcnt lgkmcnt(0)
	v_add_f32_e32 v1, v1, v23
	ds_bpermute_b32 v23, v43, v1
	s_nop 2
	s_waitcnt lgkmcnt(0)
	v_add_f32_e32 v1, v1, v23
	ds_bpermute_b32 v23, v44, v1
	s_nop 2
	s_waitcnt lgkmcnt(0)
	v_add_f32_e32 v1, v1, v23
	ds_bpermute_b32 v23, v45, v1
	s_nop 2
	s_waitcnt lgkmcnt(0)
	v_add_f32_e32 v1, v1, v23
	ds_bpermute_b32 v23, v46, v1
	s_waitcnt lgkmcnt(0)
	v_add_f32_e32 v1, v1, v23
	v_fmamk_f32 v1, v1, 0x3a800000, v188
	v_cmp_gt_f32_e32 vcc, s0, v1
	v_readlane_b32 s0, v245, 5
	v_readlane_b32 s1, v245, 6
	v_mul_f32_e32 v23, 0x4b800000, v1
	v_cndmask_b32_e32 v1, v1, v23, vcc
	v_lshl_add_u64 v[42:43], v[18:19], 2, s[0:1]
	s_mov_b64 s[0:1], 0x1000
	v_lshl_add_u64 v[18:19], v[42:43], 0, s[0:1]
	v_readlane_b32 s0, v247, 56
	v_readlane_b32 s1, v247, 57
	v_rsq_f32_e32 v1, v1
	s_nop 0
	v_lshl_add_u64 v[36:37], s[0:1], 0, v[34:35]
	v_lshl_add_u64 v[34:35], v[42:43], 0, v[20:21]
	v_lshl_add_u64 v[20:21], v[18:19], 0, v[20:21]
	global_load_dwordx4 v[46:49], v[20:21], off
	global_load_dwordx4 v[42:45], v[34:35], off
	global_load_dwordx4 v[64:67], v[32:33], off offset:1024
	global_load_dwordx4 v[68:71], v[34:35], off offset:1024
	v_lshl_add_u64 v[72:73], v[18:19], 0, v[26:27]
	global_load_dwordx4 v[74:77], v[72:73], off
	global_load_dwordx4 v[78:81], v[32:33], off offset:2048
	global_load_dwordx4 v[82:85], v[34:35], off offset:2048
	v_lshl_add_u64 v[86:87], v[18:19], 0, v[28:29]
	global_load_dwordx4 v[88:91], v[86:87], off
	global_load_dwordx4 v[92:95], v[32:33], off offset:3072
	global_load_dwordx4 v[96:99], v[34:35], off offset:3072
	v_lshl_add_u64 v[100:101], v[18:19], 0, v[30:31]
	global_load_dwordx4 v[102:105], v[100:101], off
	v_mul_f32_e32 v23, 0x45800000, v1
	v_cndmask_b32_e32 v24, v1, v23, vcc
	v_pk_mul_f32 v[14:15], v[14:15], v[24:25] op_sel_hi:[1,0]
	v_mov_b32_e32 v23, v0
	v_pk_mul_f32 v[10:11], v[10:11], v[24:25] op_sel_hi:[1,0]
	v_pk_mul_f32 v[12:13], v[12:13], v[24:25] op_sel_hi:[1,0]
	v_pk_mul_f32 v[6:7], v[6:7], v[24:25] op_sel_hi:[1,0]
	v_pk_mul_f32 v[8:9], v[8:9], v[24:25] op_sel_hi:[1,0]
	v_pk_mul_f32 v[2:3], v[2:3], v[24:25] op_sel_hi:[1,0]
	v_pk_mul_f32 v[4:5], v[4:5], v[24:25] op_sel_hi:[1,0]
	s_mov_b64 s[0:1], 0
	s_waitcnt vmcnt(0)
	v_pk_mul_f32 v[14:15], v[38:39], v[14:15]
	s_nop 0
	v_pk_add_f32 v[20:21], v[46:47], 1.0 op_sel_hi:[1,0]
	s_nop 0
	v_pk_fma_f32 v[14:15], v[20:21], v[14:15], v[42:43]
	s_nop 0
	v_cvt_pk_bf16_f32 v20, v14, v15
	v_pk_mul_f32 v[14:15], v[16:17], v[24:25] op_sel_hi:[1,0]
	v_pk_add_f32 v[16:17], v[48:49], 1.0 op_sel_hi:[1,0]
	v_pk_mul_f32 v[14:15], v[40:41], v[14:15]
	s_nop 0
	v_pk_fma_f32 v[14:15], v[16:17], v[14:15], v[44:45]
	v_lshl_add_u64 v[16:17], v[18:19], 0, v[26:27]
	v_cvt_pk_bf16_f32 v21, v14, v15
	v_lshl_add_u64 v[14:15], v[36:37], 0, v[22:23]
	global_store_dwordx2 v[14:15], v[20:21], off
	s_nop 0
	s_nop 0
	v_pk_mul_f32 v[10:11], v[64:65], v[10:11]
	v_pk_mul_f32 v[12:13], v[66:67], v[12:13]
	s_nop 0
	v_pk_add_f32 v[16:17], v[74:75], 1.0 op_sel_hi:[1,0]
	s_nop 0
	v_pk_fma_f32 v[10:11], v[16:17], v[10:11], v[68:69]
	v_pk_add_f32 v[16:17], v[76:77], 1.0 op_sel_hi:[1,0]
	v_cvt_pk_bf16_f32 v10, v10, v11
	v_pk_fma_f32 v[12:13], v[16:17], v[12:13], v[70:71]
	v_lshl_add_u64 v[16:17], v[18:19], 0, v[28:29]
	v_cvt_pk_bf16_f32 v11, v12, v13
	global_store_dwordx2 v[14:15], v[10:11], off offset:512
	s_nop 0
	v_lshl_add_u64 v[16:17], v[18:19], 0, v[30:31]
	s_nop 0
	v_pk_mul_f32 v[6:7], v[78:79], v[6:7]
	v_pk_mul_f32 v[8:9], v[80:81], v[8:9]
	s_nop 0
	v_pk_add_f32 v[10:11], v[88:89], 1.0 op_sel_hi:[1,0]
	s_nop 0
	v_pk_fma_f32 v[6:7], v[10:11], v[6:7], v[82:83]
	v_pk_add_f32 v[10:11], v[90:91], 1.0 op_sel_hi:[1,0]
	v_cvt_pk_bf16_f32 v6, v6, v7
	v_pk_fma_f32 v[8:9], v[10:11], v[8:9], v[84:85]
	s_nop 0
	v_cvt_pk_bf16_f32 v7, v8, v9
	global_store_dwordx2 v[14:15], v[6:7], off offset:1024
	s_nop 0
	s_nop 0
	v_pk_mul_f32 v[2:3], v[92:93], v[2:3]
	v_pk_mul_f32 v[4:5], v[94:95], v[4:5]
	s_nop 0
	v_pk_add_f32 v[6:7], v[102:103], 1.0 op_sel_hi:[1,0]
	s_nop 0
	v_pk_fma_f32 v[2:3], v[2:3], v[6:7], v[96:97]
	v_pk_add_f32 v[6:7], v[104:105], 1.0 op_sel_hi:[1,0]
	v_cvt_pk_bf16_f32 v2, v2, v3
	v_pk_fma_f32 v[4:5], v[4:5], v[6:7], v[98:99]
	s_nop 0
	v_cvt_pk_bf16_f32 v3, v4, v5
	global_store_dwordx2 v[14:15], v[2:3], off offset:1536
